# v42 + dependency polls at s_sleep 2 instead of s_sleep 8 (50 sites)
# baseline (speedup 1.0000x reference)
.LBB0_602:
	global_load_dword v0, v129, s[76:77] offset:2048 sc1
	s_mov_b64 s[12:13], -1
	s_waitcnt vmcnt(0)
	v_cmp_le_u32_e32 vcc, s60, v0
	s_cbranch_vccnz .LBB0_601
	s_cmp_lg_u32 s0, 0
	s_sleep 2
	s_cbranch_scc0 .LBB0_600
	global_load_dword v0, v129, s[76:77] offset:2048 sc1
	s_waitcnt vmcnt(0)
	v_cmp_gt_u32_e32 vcc, s60, v0
	s_cbranch_vccz .LBB0_601
	s_sleep 2
	global_load_dword v0, v129, s[76:77] offset:2048 sc1
	s_waitcnt vmcnt(0)
	v_cmp_gt_u32_e32 vcc, s60, v0
	s_cbranch_vccz .LBB0_601
	s_sleep 2
	global_load_dword v0, v129, s[76:77] offset:2048 sc1
	s_waitcnt vmcnt(0)
	v_cmp_gt_u32_e32 vcc, s60, v0
	s_cbranch_vccz .LBB0_601
	s_sleep 2
	global_load_dword v0, v129, s[76:77] offset:2048 sc1
	s_waitcnt vmcnt(0)
	v_cmp_gt_u32_e32 vcc, s60, v0
	s_cbranch_vccz .LBB0_601
	s_sleep 2
	global_load_dword v0, v129, s[76:77] offset:2048 sc1
	s_waitcnt vmcnt(0)
	v_cmp_gt_u32_e32 vcc, s60, v0
	s_cbranch_vccz .LBB0_601
	s_sleep 2
	global_load_dword v0, v129, s[76:77] offset:2048 sc1
	s_waitcnt vmcnt(0)
	v_cmp_gt_u32_e32 vcc, s60, v0
	s_cbranch_vccz .LBB0_601
	s_sleep 2
	global_load_dword v0, v129, s[76:77] offset:2048 sc1
	s_waitcnt vmcnt(0)
	v_cmp_gt_u32_e32 vcc, s60, v0
	s_cbranch_vccz .LBB0_601
	s_sleep 2
	s_add_i32 s0, s0, -8
	s_mov_b64 s[12:13], 0
	s_branch .LBB0_601

.LBB0_625:
	global_load_dword v3, v[0:1], off sc1
	s_or_b64 s[16:17], s[16:17], exec
	s_waitcnt vmcnt(0)
	v_cmp_gt_u32_e32 vcc, 16, v3
	s_and_saveexec_b64 s[18:19], vcc
	s_cbranch_execz .LBB0_624
	s_cmp_lg_u32 s0, 0
	s_sleep 2
	s_cbranch_scc0 .LBB0_635
	global_load_dword v3, v[0:1], off sc1
	s_mov_b64 s[30:31], -1
	s_waitcnt vmcnt(0)
	v_cmp_gt_u32_e32 vcc, 16, v3
	s_and_saveexec_b64 s[20:21], vcc
	s_cbranch_execz .LBB0_622
	s_sleep 2
	global_load_dword v3, v[0:1], off sc1
	s_mov_b64 s[34:35], -1
	s_waitcnt vmcnt(0)
	v_cmp_gt_u32_e32 vcc, 16, v3
	s_and_saveexec_b64 s[30:31], vcc
	s_cbranch_execz .LBB0_621
	s_sleep 2
	global_load_dword v3, v[0:1], off sc1
	s_mov_b64 s[38:39], -1
	s_waitcnt vmcnt(0)
	v_cmp_gt_u32_e32 vcc, 16, v3
	s_and_saveexec_b64 s[34:35], vcc
	s_cbranch_execz .LBB0_620
	s_sleep 2
	global_load_dword v3, v[0:1], off sc1
	s_mov_b64 s[40:41], -1
	s_waitcnt vmcnt(0)
	v_cmp_gt_u32_e32 vcc, 16, v3
	s_and_saveexec_b64 s[38:39], vcc
	s_cbranch_execz .LBB0_619
	s_sleep 2
	global_load_dword v3, v[0:1], off sc1
	s_mov_b64 s[42:43], -1
	s_waitcnt vmcnt(0)
	v_cmp_gt_u32_e32 vcc, 16, v3
	s_and_saveexec_b64 s[40:41], vcc
	s_cbranch_execz .LBB0_618
	s_sleep 2
	global_load_dword v3, v[0:1], off sc1
	s_mov_b64 s[46:47], -1
	s_waitcnt vmcnt(0)
	v_cmp_gt_u32_e32 vcc, 16, v3
	s_and_saveexec_b64 s[42:43], vcc
	s_cbranch_execz .LBB0_617
	s_sleep 2
	global_load_dword v3, v[0:1], off sc1
	s_waitcnt vmcnt(0)
	v_cmp_gt_u32_e32 vcc, 16, v3
	s_and_saveexec_b64 s[48:49], vcc
	s_cbranch_execz .LBB0_616
	s_add_i32 s0, s0, -8
	s_xor_b64 s[46:47], exec, -1
	s_sleep 2
	s_branch .LBB0_616

.Lpk_wait:
	global_load_dword v1, v2, s[56:57] sc1
	s_waitcnt vmcnt(0)
	v_readfirstlane_b32 s14, v1
	s_nop 1
	s_cmp_gt_u32 s14, 3
	s_cbranch_scc1 .Lpk_go
	s_sleep 2
	s_branch .Lpk_wait

.Lpk_sleep:
	s_sleep 2
	s_branch .Lpk_top

.LBB0_1215:
	global_load_dword v3, v[0:1], off sc1
	s_or_b64 s[16:17], s[16:17], exec
	s_waitcnt vmcnt(0)
	v_cmp_gt_u32_e32 vcc, 16, v3
	s_and_saveexec_b64 s[18:19], vcc
	s_cbranch_execz .LBB0_1214
	s_cmp_lg_u32 s4, 0
	s_sleep 2
	s_cbranch_scc0 .LBB0_1225
	global_load_dword v3, v[0:1], off sc1
	s_mov_b64 s[30:31], -1
	s_waitcnt vmcnt(0)
	v_cmp_gt_u32_e32 vcc, 16, v3
	s_and_saveexec_b64 s[20:21], vcc
	s_cbranch_execz .LBB0_1212
	s_sleep 2
	global_load_dword v3, v[0:1], off sc1
	s_mov_b64 s[34:35], -1
	s_waitcnt vmcnt(0)
	v_cmp_gt_u32_e32 vcc, 16, v3
	s_and_saveexec_b64 s[30:31], vcc
	s_cbranch_execz .LBB0_1211
	s_sleep 2
	global_load_dword v3, v[0:1], off sc1
	s_mov_b64 s[36:37], -1
	s_waitcnt vmcnt(0)
	v_cmp_gt_u32_e32 vcc, 16, v3
	s_and_saveexec_b64 s[34:35], vcc
	s_cbranch_execz .LBB0_1210
	s_sleep 2
	global_load_dword v3, v[0:1], off sc1
	s_mov_b64 s[38:39], -1
	s_waitcnt vmcnt(0)
	v_cmp_gt_u32_e32 vcc, 16, v3
	s_and_saveexec_b64 s[36:37], vcc
	s_cbranch_execz .LBB0_1209
	s_sleep 2
	global_load_dword v3, v[0:1], off sc1
	s_mov_b64 s[40:41], -1
	s_waitcnt vmcnt(0)
	v_cmp_gt_u32_e32 vcc, 16, v3
	s_and_saveexec_b64 s[38:39], vcc
	s_cbranch_execz .LBB0_1208
	s_sleep 2
	global_load_dword v3, v[0:1], off sc1
	s_mov_b64 s[42:43], -1
	s_waitcnt vmcnt(0)
	v_cmp_gt_u32_e32 vcc, 16, v3
	s_and_saveexec_b64 s[40:41], vcc
	s_cbranch_execz .LBB0_1207
	s_sleep 2
	global_load_dword v3, v[0:1], off sc1
	s_waitcnt vmcnt(0)
	v_cmp_gt_u32_e32 vcc, 16, v3
	s_and_saveexec_b64 s[44:45], vcc
	s_cbranch_execz .LBB0_1206
	s_add_i32 s4, s4, -8
	s_xor_b64 s[42:43], exec, -1
	s_sleep 2
	s_branch .LBB0_1206

.LBB0_1312:
	global_load_dword v4, v[0:1], off sc1
	s_or_b64 s[28:29], s[28:29], exec
	s_waitcnt vmcnt(0)
	v_cmp_gt_u32_e32 vcc, 4, v4
	s_and_saveexec_b64 s[30:31], vcc
	s_cbranch_execz .LBB0_1311
	s_cmp_lg_u32 s18, 0
	s_sleep 2
	s_cbranch_scc0 .LBB0_1322
	global_load_dword v4, v[0:1], off sc1
	s_mov_b64 s[36:37], -1
	s_waitcnt vmcnt(0)
	v_cmp_gt_u32_e32 vcc, 4, v4
	s_and_saveexec_b64 s[34:35], vcc
	s_cbranch_execz .LBB0_1309
	s_sleep 2
	global_load_dword v4, v[0:1], off sc1
	s_mov_b64 s[38:39], -1
	s_waitcnt vmcnt(0)
	v_cmp_gt_u32_e32 vcc, 4, v4
	s_and_saveexec_b64 s[36:37], vcc
	s_cbranch_execz .LBB0_1308
	s_sleep 2
	global_load_dword v4, v[0:1], off sc1
	s_mov_b64 s[40:41], -1
	s_waitcnt vmcnt(0)
	v_cmp_gt_u32_e32 vcc, 4, v4
	s_and_saveexec_b64 s[38:39], vcc
	s_cbranch_execz .LBB0_1307
	s_sleep 2
	global_load_dword v4, v[0:1], off sc1
	s_mov_b64 s[42:43], -1
	s_waitcnt vmcnt(0)
	v_cmp_gt_u32_e32 vcc, 4, v4
	s_and_saveexec_b64 s[40:41], vcc
	s_cbranch_execz .LBB0_1306
	s_sleep 2
	global_load_dword v4, v[0:1], off sc1
	s_mov_b64 s[44:45], -1
	s_waitcnt vmcnt(0)
	v_cmp_gt_u32_e32 vcc, 4, v4
	s_and_saveexec_b64 s[42:43], vcc
	s_cbranch_execz .LBB0_1305
	s_sleep 2
	global_load_dword v4, v[0:1], off sc1
	s_mov_b64 s[46:47], -1
	s_waitcnt vmcnt(0)
	v_cmp_gt_u32_e32 vcc, 4, v4
	s_and_saveexec_b64 s[44:45], vcc
	s_cbranch_execz .LBB0_1304
	s_sleep 2
	global_load_dword v4, v[0:1], off sc1
	s_waitcnt vmcnt(0)
	v_cmp_gt_u32_e32 vcc, 4, v4
	s_and_saveexec_b64 s[48:49], vcc
	s_cbranch_execz .LBB0_1303
	s_add_i32 s18, s18, -8
	s_xor_b64 s[46:47], exec, -1
	s_sleep 2
	s_branch .LBB0_1303

.LBB0_1391:
	s_andn2_b64 vcc, exec, s[8:9]
	s_cbranch_vccnz .LBB0_1388
	s_cmp_lg_u32 s3, 0
	s_sleep 2
	s_cbranch_scc0 .LBB0_1387
	global_load_dword v1, v0, s[4:5] sc1
	s_waitcnt vmcnt(0)
	v_cmp_lt_u32_e32 vcc, 3, v1
	v_cmp_gt_u32_e64 s[6:7], 4, v1
	s_cbranch_vccz .LBB0_1395
	global_load_dword v1, v0, s[4:5] offset:2048 sc1
	s_waitcnt vmcnt(0)
	v_cmp_gt_u32_e64 s[6:7], 4, v1
.LBB0_1395:
	s_andn2_b64 vcc, exec, s[6:7]
	s_mov_b64 s[6:7], -1
	s_cbranch_vccnz .LBB0_1388
	s_sleep 2
	global_load_dword v1, v0, s[4:5] sc1
	s_waitcnt vmcnt(0)
	v_cmp_lt_u32_e32 vcc, 3, v1
	v_cmp_gt_u32_e64 s[6:7], 4, v1
	s_cbranch_vccz .LBB0_1398
	global_load_dword v1, v0, s[4:5] offset:2048 sc1
	s_waitcnt vmcnt(0)
	v_cmp_gt_u32_e64 s[6:7], 4, v1

.LBB0_1413:
	s_andn2_b64 vcc, exec, s[6:7]
	s_mov_b64 s[6:7], -1
	s_cbranch_vccnz .LBB0_1388
	s_sleep 2
	s_add_i32 s3, s3, -8
	s_mov_b64 s[6:7], 0
	s_branch .LBB0_1388

.LBB0_1440:
	global_load_dword v1, v0, s[76:77] offset:2816 sc1
	s_mov_b64 s[4:5], -1
	s_waitcnt vmcnt(0)
	v_cmp_lt_u32_e32 vcc, s10, v1
	s_cbranch_vccnz .LBB0_1439
	s_cmp_lg_u32 s11, 0
	s_sleep 2
	s_cbranch_scc0 .LBB0_1438
	global_load_dword v1, v0, s[76:77] offset:2816 sc1
	s_waitcnt vmcnt(0)
	v_cmp_gt_u32_e32 vcc, s12, v1
	s_cbranch_vccz .LBB0_1439
	s_sleep 2
	global_load_dword v1, v0, s[76:77] offset:2816 sc1
	s_waitcnt vmcnt(0)
	v_cmp_gt_u32_e32 vcc, s12, v1
	s_cbranch_vccz .LBB0_1439
	s_sleep 2
	global_load_dword v1, v0, s[76:77] offset:2816 sc1
	s_waitcnt vmcnt(0)
	v_cmp_gt_u32_e32 vcc, s12, v1
	s_cbranch_vccz .LBB0_1439
	s_sleep 2
	global_load_dword v1, v0, s[76:77] offset:2816 sc1
	s_waitcnt vmcnt(0)
	v_cmp_gt_u32_e32 vcc, s12, v1
	s_cbranch_vccz .LBB0_1439
	s_sleep 2
	global_load_dword v1, v0, s[76:77] offset:2816 sc1
	s_waitcnt vmcnt(0)
	v_cmp_gt_u32_e32 vcc, s12, v1
	s_cbranch_vccz .LBB0_1439
	s_sleep 2
	global_load_dword v1, v0, s[76:77] offset:2816 sc1
	s_waitcnt vmcnt(0)
	v_cmp_gt_u32_e32 vcc, s12, v1
	s_cbranch_vccz .LBB0_1439
	s_sleep 2
	global_load_dword v1, v0, s[76:77] offset:2816 sc1
	s_waitcnt vmcnt(0)
	v_cmp_gt_u32_e32 vcc, s12, v1
	s_cbranch_vccz .LBB0_1439
	s_sleep 2
	s_add_i32 s11, s11, -8
	s_mov_b64 s[4:5], 0
	s_branch .LBB0_1439
